# MLA loop: tile counter stepped once per 6 tiles, first-piece M0 written at the end of the previous tile (one s_nop and one s_add fewer per tile)
# baseline (speedup 1.0000x reference)
; #define AT_QK_LD0(kb_) do { if constexpr (NEGM) { const LAS unsigned char* kbp_ = Kl + (kb_) * KBUF + r32 * KROWB + hi * 16; AT_KLD2(0); __builtin_amdgcn_sched_barrier(0); } } while (0)
; template <int DQK, int DV, int RH, bool NEGM> ...
;     ...
;     const int NT = nkv / 64;
;     AT_GLOAD(0); AT_LSTORE(0, 0); __syncthreads();
;     int vs_prev = 2, vs_cur = 0, vs_next = 1;
;     if (!grpB) {
;         for (int t = 0; t < NT; ++t) {
;             const int kb = t & 1;
;             if (t + 1 < NT) AT_GLOAD(t + 1);
;             f32x16 p[RH][2];
;             AT_QK_LD0(kb); AT_QK(kb); AT_VLOAD(vs_cur); AT_SOFTMAX(); AT_PV(vs_cur);
;             if (t + 1 < NT) AT_LSTORE(kb ^ 1, vs_next);
.LBB0_881:
	s_or_b64 exec, exec, s[42:43]
	v_pk_add_f32 v[48:49], v[48:49], v[54:55]
	v_pk_add_f32 v[64:65], v[128:129], v[64:65]
	v_pk_add_f32 v[48:49], v[58:59], v[48:49] op_sel_hi:[0,1]
	v_pk_add_f32 v[52:53], v[52:53], v[56:57]
	v_pk_add_f32 v[48:49], v[64:65], v[48:49]
	v_pk_add_f32 v[70:71], v[118:119], v[70:71]
	v_pk_add_f32 v[48:49], v[52:53], v[48:49]
	v_add_u32_e32 v54, v136, v135
	v_pk_add_f32 v[150:151], v[70:71], v[48:49]
	v_add_u32_e32 v48, 0x8c00, v166
	s_waitcnt vmcnt(0)
	ds_write2_b64 v48, v[74:75], v[76:77] offset1:2
	v_mul_lo_u32 v48, v54, 12
	v_sub_u32_e32 v52, v133, v48
	s_lshr_b32 s21, s61, 4
	v_lshlrev_b32_e32 v48, 3, v52
	v_lshlrev_b32_e32 v175, 4, v52
	v_mov_b64_e32 v[52:53], s[40:41]
	s_and_b32 s42, s21, 7
	v_mul_lo_u32 v174, v54, s56
	v_mad_i64_i32 v[54:55], s[40:41], v54, s51, v[52:53]
	v_pk_add_f32 v[50:51], v[50:51], v[62:63]
	v_ashrrev_i32_e32 v49, 31, v48
	v_mad_u64_u32 v[54:55], s[40:41], s42, v163, v[54:55]
	v_pk_add_f32 v[66:67], v[130:131], v[66:67]
	v_pk_add_f32 v[50:51], v[58:59], v[50:51] op_sel_hi:[0,1]
	v_lshl_add_u64 v[48:49], v[48:49], 1, v[54:55]
	v_pk_add_f32 v[56:57], v[116:117], v[68:69]
	v_pk_add_f32 v[50:51], v[66:67], v[50:51]
	v_mov_b32_e32 v154, v48
	v_mad_i64_i32 v[48:49], s[40:41], v59, s51, v[52:53]
	v_pk_add_f32 v[60:61], v[60:61], v[72:73]
	v_pk_add_f32 v[50:51], v[56:57], v[50:51]
	s_lshl_b32 s43, s42, 6
	v_mad_u64_u32 v[48:49], s[40:41], s42, v163, v[48:49]
	v_pk_add_f32 v[152:153], v[60:61], v[50:51]
	v_lshlrev_b32_e32 v50, 3, v112
	s_add_i32 s40, s47, s43
	v_ashrrev_i32_e32 v51, 31, v50
	s_ashr_i32 s41, s40, 31
	v_lshl_add_u64 v[48:49], v[50:51], 1, v[48:49]
	s_lshl_b64 s[40:41], s[40:41], 13
	v_and_b32_e32 v50, 7, v132
	v_mov_b32_e32 v156, v48
	v_lshl_add_u64 v[48:49], v[78:79], 0, s[40:41]
	v_lshlrev_b32_e32 v148, 4, v50
	v_lshl_add_u64 v[48:49], v[48:49], 0, v[148:149]
	v_mul_u32_u24_e32 v173, 0x90, v134
	s_mov_b32 s21, 1
	v_mov_b32_e32 v158, v48
	s_mov_b32 s42, 2
	s_mov_b32 s43, 1
	s_waitcnt lgkmcnt(0)
	s_barrier
	s_mov_b64 s[98:99], s[28:29]
	s_mov_b64 s[100:101], s[30:31]
	v_add_u32_e32 v244, v174, v175
	v_add_u32_e32 v245, v171, v172
	s_mov_b32 s71, 0x13b13b14
	s_mov_b32 s72, 0x15555556
	v_add_u32_e32 v148, s79, v184
	v_mul_hi_u32 v160, v148, s71
	v_mul_u32_u24_e32 v161, 13, v160
	v_sub_u32_e32 v161, v148, v161
	v_min_u32_e32 v161, 11, v161
	v_mul_u32_u24_e32 v160, 0x600, v160
	v_lshl_add_u32 v241, v161, 4, v160
	v_mul_hi_u32 v160, v148, s72
	v_mul_u32_u24_e32 v161, 12, v160
	v_sub_u32_e32 v161, v148, v161
	v_mul_u32_u24_e32 v160, 0x600, v160
	v_lshl_add_u32 v160, v161, 4, v160
	v_sub_u32_e32 v241, v241, v160
	v_add_u32_e32 v241, v241, v154
	v_add_u32_e32 v148, 0x200, v148
	v_mul_hi_u32 v160, v148, s71
	v_mul_u32_u24_e32 v161, 13, v160
	v_sub_u32_e32 v161, v148, v161
	v_min_u32_e32 v161, 11, v161
	v_mul_u32_u24_e32 v160, 0x600, v160
	v_lshl_add_u32 v242, v161, 4, v160
	v_mul_hi_u32 v160, v148, s72
	v_mul_u32_u24_e32 v161, 12, v160
	v_sub_u32_e32 v161, v148, v161
	v_mul_u32_u24_e32 v160, 0x600, v160
	v_lshl_add_u32 v160, v161, 4, v160
	v_sub_u32_e32 v242, v242, v160
	v_add_u32_e32 v242, v242, v156
	s_lshl_b32 s70, s79, 4
	s_add_i32 s73, s70, 0x2000
	s_cmpk_lt_u32 s79, 0x140
	s_cselect_b32 s73, s73, 0x12000
	s_cselect_b32 s74, 0x3400, 0
	s_mov_b32 m0, s70
	s_cmp_eq_u32 s65, 0
	s_cbranch_scc0 .Lmlac_loop

.Lmla_renorm_back:
	ds_read_b128 v[48:51], v169 offset:13312
	ds_read_b128 v[52:55], v169 offset:13344
	ds_read_b128 v[116:119], v169 offset:19968
	ds_read_b128 v[120:123], v169 offset:20000
	global_load_lds_dwordx4 v241, s[98:99]
	s_mov_b32 m0, s73
	global_load_dwordx4 v[112:115], v158, s[100:101]
	global_load_lds_dwordx4 v242, s[98:99]
	s_add_u32 s98, s98, 0x18000
	s_addc_u32 s99, s99, 0
	s_waitcnt lgkmcnt(3)
	v_mfma_f32_32x32x16_bf16 v[64:79], v[48:51], v[100:103], v[32:47]
	ds_read_b128 v[124:127], v169 offset:13376
	ds_read_b128 v[128:131], v169 offset:13408
	ds_read_b128 v[132:135], v169 offset:20032
	ds_read_b128 v[136:139], v169 offset:20064
	s_waitcnt lgkmcnt(4)
	v_mfma_f32_32x32x16_bf16 v[64:79], v[52:55], v[96:99], v[64:79]
	v_mfma_f32_32x32x16_bf16 v[48:63], v[116:119], v[100:103], v[32:47]
	v_mfma_f32_32x32x16_bf16 v[48:63], v[120:123], v[96:99], v[48:63]
	s_waitcnt lgkmcnt(1)
	v_mfma_f32_32x32x16_bf16 v[64:79], v[124:127], v[92:95], v[64:79]
	v_mfma_f32_32x32x16_bf16 v[48:63], v[132:135], v[92:95], v[48:63]
	v_mfma_f32_32x32x16_bf16 v[64:79], v[128:131], v[88:91], v[64:79]
	ds_read_b128 v[116:119], v169 offset:13440
	ds_read_b128 v[120:123], v169 offset:13472
	ds_read_b128 v[128:131], v169 offset:20096
	ds_read_b128 v[176:179], v169 offset:20128
	s_waitcnt lgkmcnt(3)
	v_mfma_f32_32x32x16_bf16 v[48:63], v[136:139], v[88:91], v[48:63]
	v_mfma_f32_32x32x16_bf16 v[64:79], v[116:119], v[84:87], v[64:79]
	ds_read_b128 v[136:139], v170 offset:35840
	ds_read_b128 v[124:127], v170 offset:35872
	s_waitcnt lgkmcnt(3)
	v_mfma_f32_32x32x16_bf16 v[48:63], v[128:131], v[84:87], v[48:63]
	v_mfma_f32_32x32x16_bf16 v[64:79], v[120:123], v[80:83], v[64:79]
	ds_read_b128 v[132:135], v170 offset:35904
	ds_read_b128 v[120:123], v170 offset:35936
	ds_read_b128 v[144:147], v170 offset:40448
	ds_read_b128 v[140:143], v170 offset:40480
	ds_read_b128 v[128:131], v170 offset:40512
	ds_read_b128 v[116:119], v170 offset:40544
	s_waitcnt lgkmcnt(8)
	v_mfma_f32_32x32x16_bf16 v[48:63], v[176:179], v[80:83], v[48:63]
	s_nop 4
	v_exp_f32_e32 v160, v64
	v_exp_f32_e32 v161, v65
	v_exp_f32_e32 v64, v66
	v_exp_f32_e32 v65, v67
	v_exp_f32_e32 v68, v68
	v_exp_f32_e32 v69, v69
	v_exp_f32_e32 v66, v70
	v_exp_f32_e32 v67, v71
	v_cvt_pk_bf16_f32 v176, v160, v161
	v_cvt_pk_bf16_f32 v177, v64, v65
	v_cvt_pk_bf16_f32 v178, v68, v69
	v_cvt_pk_bf16_f32 v179, v66, v67
	v_exp_f32_e32 v70, v74
	v_exp_f32_e32 v71, v75
	s_waitcnt lgkmcnt(0)
	v_mfma_f32_32x32x16_bf16 v[16:31], v[136:139], v[176:179], v[16:31]
	v_exp_f32_e32 v136, v72
	v_exp_f32_e32 v137, v73
	v_exp_f32_e32 v74, v76
	v_exp_f32_e32 v75, v77
	v_exp_f32_e32 v72, v78
	v_exp_f32_e32 v73, v79
	v_exp_f32_e32 v76, v48
	v_mfma_f32_32x32x16_bf16 v[0:15], v[144:147], v[176:179], v[0:15]
	v_cvt_pk_bf16_f32 v144, v136, v137
	v_cvt_pk_bf16_f32 v145, v70, v71
	v_cvt_pk_bf16_f32 v146, v74, v75
	v_cvt_pk_bf16_f32 v147, v72, v73
	v_exp_f32_e32 v77, v49
	v_exp_f32_e32 v48, v50
	v_exp_f32_e32 v49, v51
	v_mfma_f32_32x32x16_bf16 v[16:31], v[124:127], v[144:147], v[16:31]
	v_exp_f32_e32 v52, v52
	v_exp_f32_e32 v53, v53
	v_exp_f32_e32 v50, v54
	v_exp_f32_e32 v51, v55
	v_cvt_pk_bf16_f32 v124, v76, v77
	v_cvt_pk_bf16_f32 v125, v48, v49
	v_cvt_pk_bf16_f32 v126, v52, v53
	v_mfma_f32_32x32x16_bf16 v[0:15], v[140:143], v[144:147], v[0:15]
	v_cvt_pk_bf16_f32 v127, v50, v51
	v_exp_f32_e32 v78, v56
	v_exp_f32_e32 v79, v57
	v_exp_f32_e32 v54, v58
	v_exp_f32_e32 v55, v59
	v_exp_f32_e32 v58, v60
	v_exp_f32_e32 v59, v61
	v_mfma_f32_32x32x16_bf16 v[16:31], v[132:135], v[124:127], v[16:31]
	v_exp_f32_e32 v56, v62
	v_exp_f32_e32 v57, v63
	v_cvt_pk_bf16_f32 v60, v78, v79
	v_cvt_pk_bf16_f32 v61, v54, v55
	v_cvt_pk_bf16_f32 v62, v58, v59
	v_cvt_pk_bf16_f32 v63, v56, v57
	v_mfma_f32_32x32x16_bf16 v[0:15], v[128:131], v[124:127], v[0:15]
	v_mfma_f32_32x32x16_bf16 v[16:31], v[120:123], v[60:63], v[16:31]
	v_mfma_f32_32x32x16_bf16 v[0:15], v[116:119], v[60:63], v[0:15]
	s_waitcnt vmcnt(0)
	ds_write2_b64 v247, v[112:113], v[114:115] offset1:2
	v_pk_add_f32 v[48:49], v[64:65], v[48:49]
	v_pk_add_f32 v[60:61], v[160:161], v[76:77]
	v_pk_add_f32 v[48:49], v[152:153], v[48:49]
	v_pk_add_f32 v[50:51], v[66:67], v[50:51]
	v_pk_add_f32 v[60:61], v[150:151], v[60:61]
	v_pk_add_f32 v[52:53], v[68:69], v[52:53]
	v_pk_add_f32 v[48:49], v[50:51], v[48:49]
	v_pk_add_f32 v[50:51], v[70:71], v[54:55]
	v_pk_add_f32 v[52:53], v[52:53], v[60:61]
	v_pk_add_f32 v[60:61], v[136:137], v[78:79]
	v_pk_add_f32 v[48:49], v[50:51], v[48:49]
	v_pk_add_f32 v[50:51], v[72:73], v[56:57]
	v_pk_add_f32 v[52:53], v[60:61], v[52:53]
	v_pk_add_f32 v[58:59], v[74:75], v[58:59]
	v_pk_add_f32 v[152:153], v[50:51], v[48:49]
	v_pk_add_f32 v[150:151], v[58:59], v[52:53]
	s_add_i32 m0, s70, 13312
	s_waitcnt lgkmcnt(0)
	s_barrier
	ds_read_b128 v[48:51], v169
	ds_read_b128 v[52:55], v169 offset:32
	ds_read_b128 v[116:119], v169 offset:6656
	ds_read_b128 v[120:123], v169 offset:6688
	global_load_lds_dwordx4 v241, s[98:99]
	s_add_i32 m0, s73, s74
	global_load_dwordx4 v[112:115], v158, s[100:101] offset:128
	global_load_lds_dwordx4 v242, s[98:99]
	s_add_u32 s98, s98, 0x18000
	s_addc_u32 s99, s99, 0
	s_waitcnt lgkmcnt(3)
	v_mfma_f32_32x32x16_bf16 v[64:79], v[48:51], v[100:103], v[32:47]
	ds_read_b128 v[124:127], v169 offset:64
	ds_read_b128 v[128:131], v169 offset:96
	ds_read_b128 v[132:135], v169 offset:6720
	ds_read_b128 v[136:139], v169 offset:6752
	s_waitcnt lgkmcnt(4)
	v_mfma_f32_32x32x16_bf16 v[64:79], v[52:55], v[96:99], v[64:79]
	v_mfma_f32_32x32x16_bf16 v[48:63], v[116:119], v[100:103], v[32:47]
	v_mfma_f32_32x32x16_bf16 v[48:63], v[120:123], v[96:99], v[48:63]
	s_waitcnt lgkmcnt(1)
	v_mfma_f32_32x32x16_bf16 v[64:79], v[124:127], v[92:95], v[64:79]
	v_mfma_f32_32x32x16_bf16 v[48:63], v[132:135], v[92:95], v[48:63]
	v_mfma_f32_32x32x16_bf16 v[64:79], v[128:131], v[88:91], v[64:79]
	ds_read_b128 v[116:119], v169 offset:128
	ds_read_b128 v[120:123], v169 offset:160
	ds_read_b128 v[128:131], v169 offset:6784
	ds_read_b128 v[176:179], v169 offset:6816
	s_waitcnt lgkmcnt(3)
	v_mfma_f32_32x32x16_bf16 v[48:63], v[136:139], v[88:91], v[48:63]
	v_mfma_f32_32x32x16_bf16 v[64:79], v[116:119], v[84:87], v[64:79]
	ds_read_b128 v[136:139], v170 offset:45056
	ds_read_b128 v[124:127], v170 offset:45088
	s_waitcnt lgkmcnt(3)
	v_mfma_f32_32x32x16_bf16 v[48:63], v[128:131], v[84:87], v[48:63]
	v_mfma_f32_32x32x16_bf16 v[64:79], v[120:123], v[80:83], v[64:79]
	ds_read_b128 v[132:135], v170 offset:45120
	ds_read_b128 v[120:123], v170 offset:45152
	ds_read_b128 v[144:147], v170 offset:49664
	ds_read_b128 v[140:143], v170 offset:49696
	ds_read_b128 v[128:131], v170 offset:49728
	ds_read_b128 v[116:119], v170 offset:49760
	s_waitcnt lgkmcnt(8)
	v_mfma_f32_32x32x16_bf16 v[48:63], v[176:179], v[80:83], v[48:63]
	s_nop 4
	v_exp_f32_e32 v160, v64
	v_exp_f32_e32 v161, v65
	v_exp_f32_e32 v64, v66
	v_exp_f32_e32 v65, v67
	v_exp_f32_e32 v68, v68
	v_exp_f32_e32 v69, v69
	v_exp_f32_e32 v66, v70
	v_exp_f32_e32 v67, v71
	v_cvt_pk_bf16_f32 v176, v160, v161
	v_cvt_pk_bf16_f32 v177, v64, v65
	v_cvt_pk_bf16_f32 v178, v68, v69
	v_cvt_pk_bf16_f32 v179, v66, v67
	v_exp_f32_e32 v70, v74
	v_exp_f32_e32 v71, v75
	s_waitcnt lgkmcnt(0)
	v_mfma_f32_32x32x16_bf16 v[16:31], v[136:139], v[176:179], v[16:31]
	v_exp_f32_e32 v136, v72
	v_exp_f32_e32 v137, v73
	v_exp_f32_e32 v74, v76
	v_exp_f32_e32 v75, v77
	v_exp_f32_e32 v72, v78
	v_exp_f32_e32 v73, v79
	v_exp_f32_e32 v76, v48
	v_mfma_f32_32x32x16_bf16 v[0:15], v[144:147], v[176:179], v[0:15]
	v_cvt_pk_bf16_f32 v144, v136, v137
	v_cvt_pk_bf16_f32 v145, v70, v71
	v_cvt_pk_bf16_f32 v146, v74, v75
	v_cvt_pk_bf16_f32 v147, v72, v73
	v_exp_f32_e32 v77, v49
	v_exp_f32_e32 v48, v50
	v_exp_f32_e32 v49, v51
	v_mfma_f32_32x32x16_bf16 v[16:31], v[124:127], v[144:147], v[16:31]
	v_exp_f32_e32 v52, v52
	v_exp_f32_e32 v53, v53
	v_exp_f32_e32 v50, v54
	v_exp_f32_e32 v51, v55
	v_cvt_pk_bf16_f32 v124, v76, v77
	v_cvt_pk_bf16_f32 v125, v48, v49
	v_cvt_pk_bf16_f32 v126, v52, v53
	v_mfma_f32_32x32x16_bf16 v[0:15], v[140:143], v[144:147], v[0:15]
	v_cvt_pk_bf16_f32 v127, v50, v51
	v_exp_f32_e32 v78, v56
	v_exp_f32_e32 v79, v57
	v_exp_f32_e32 v54, v58
	v_exp_f32_e32 v55, v59
	v_exp_f32_e32 v58, v60
	v_exp_f32_e32 v59, v61
	v_mfma_f32_32x32x16_bf16 v[16:31], v[132:135], v[124:127], v[16:31]
	v_exp_f32_e32 v56, v62
	v_exp_f32_e32 v57, v63
	v_cvt_pk_bf16_f32 v60, v78, v79
	v_cvt_pk_bf16_f32 v61, v54, v55
	v_cvt_pk_bf16_f32 v62, v58, v59
	v_cvt_pk_bf16_f32 v63, v56, v57
	v_mfma_f32_32x32x16_bf16 v[0:15], v[128:131], v[124:127], v[0:15]
	v_mfma_f32_32x32x16_bf16 v[16:31], v[120:123], v[60:63], v[16:31]
	v_mfma_f32_32x32x16_bf16 v[0:15], v[116:119], v[60:63], v[0:15]
	s_waitcnt vmcnt(0)
	ds_write2_b64 v243, v[112:113], v[114:115] offset1:2
	v_pk_add_f32 v[48:49], v[64:65], v[48:49]
	v_pk_add_f32 v[60:61], v[160:161], v[76:77]
	v_pk_add_f32 v[48:49], v[152:153], v[48:49]
	v_pk_add_f32 v[50:51], v[66:67], v[50:51]
	v_pk_add_f32 v[60:61], v[150:151], v[60:61]
	v_pk_add_f32 v[52:53], v[68:69], v[52:53]
	v_pk_add_f32 v[48:49], v[50:51], v[48:49]
	v_pk_add_f32 v[50:51], v[70:71], v[54:55]
	v_pk_add_f32 v[52:53], v[52:53], v[60:61]
	v_pk_add_f32 v[60:61], v[136:137], v[78:79]
	v_pk_add_f32 v[48:49], v[50:51], v[48:49]
	v_pk_add_f32 v[50:51], v[72:73], v[56:57]
	v_pk_add_f32 v[52:53], v[60:61], v[52:53]
	v_pk_add_f32 v[58:59], v[74:75], v[58:59]
	v_pk_add_f32 v[152:153], v[50:51], v[48:49]
	v_pk_add_f32 v[150:151], v[58:59], v[52:53]
	s_mov_b32 m0, s70
	s_cmp_lg_u32 s43, 61
	s_waitcnt lgkmcnt(0)
	s_barrier
	s_cbranch_scc0 .Lmla_exit
; #define AT_QK_LD0(kb_) do { if constexpr (NEGM) { const LAS unsigned char* kbp_ = Kl + (kb_) * KBUF + r32 * KROWB + hi * 16; AT_KLD2(0); __builtin_amdgcn_sched_barrier(0); } } while (0)
; template <int DQK, int DV, int RH, bool NEGM> ...
;     ...
;         for (int t = 0; t < NT; ++t) {
;             const int kb = t & 1;
;             if (t + 1 < NT) AT_GLOAD(t + 1);
;             f32x16 p[RH][2];
;             AT_QK_LD0(kb); AT_QK(kb); AT_VLOAD(vs_cur); AT_SOFTMAX(); AT_PV(vs_cur);
;             if (t + 1 < NT) AT_LSTORE(kb ^ 1, vs_next);
;             __syncthreads();
;             vs_prev = vs_cur; vs_cur = vs_next; vs_next = (vs_next == 2) ? 0 : vs_next + 1;
	ds_read_b128 v[48:51], v169 offset:13312
	ds_read_b128 v[52:55], v169 offset:13344
	ds_read_b128 v[116:119], v169 offset:19968
	ds_read_b128 v[120:123], v169 offset:20000
	global_load_lds_dwordx4 v241, s[98:99]
	s_mov_b32 m0, s73
	global_load_dwordx4 v[112:115], v158, s[100:101] offset:256
	global_load_lds_dwordx4 v242, s[98:99]
	s_add_u32 s98, s98, 0x18000
	s_addc_u32 s99, s99, 0
	s_waitcnt lgkmcnt(3)
	v_mfma_f32_32x32x16_bf16 v[64:79], v[48:51], v[100:103], v[32:47]
	ds_read_b128 v[124:127], v169 offset:13376
	ds_read_b128 v[128:131], v169 offset:13408
	ds_read_b128 v[132:135], v169 offset:20032
	ds_read_b128 v[136:139], v169 offset:20064
	s_waitcnt lgkmcnt(4)
	v_mfma_f32_32x32x16_bf16 v[64:79], v[52:55], v[96:99], v[64:79]
	v_mfma_f32_32x32x16_bf16 v[48:63], v[116:119], v[100:103], v[32:47]
	v_mfma_f32_32x32x16_bf16 v[48:63], v[120:123], v[96:99], v[48:63]
	s_waitcnt lgkmcnt(1)
	v_mfma_f32_32x32x16_bf16 v[64:79], v[124:127], v[92:95], v[64:79]
	v_mfma_f32_32x32x16_bf16 v[48:63], v[132:135], v[92:95], v[48:63]
	v_mfma_f32_32x32x16_bf16 v[64:79], v[128:131], v[88:91], v[64:79]
	ds_read_b128 v[116:119], v169 offset:13440
	ds_read_b128 v[120:123], v169 offset:13472
	ds_read_b128 v[128:131], v169 offset:20096
	ds_read_b128 v[176:179], v169 offset:20128
	s_waitcnt lgkmcnt(3)
	v_mfma_f32_32x32x16_bf16 v[48:63], v[136:139], v[88:91], v[48:63]
	v_mfma_f32_32x32x16_bf16 v[64:79], v[116:119], v[84:87], v[64:79]
	ds_read_b128 v[136:139], v170 offset:26624
	ds_read_b128 v[124:127], v170 offset:26656
	s_waitcnt lgkmcnt(3)
	v_mfma_f32_32x32x16_bf16 v[48:63], v[128:131], v[84:87], v[48:63]
	v_mfma_f32_32x32x16_bf16 v[64:79], v[120:123], v[80:83], v[64:79]
	ds_read_b128 v[132:135], v170 offset:26688
	ds_read_b128 v[120:123], v170 offset:26720
	ds_read_b128 v[144:147], v170 offset:31232
	ds_read_b128 v[140:143], v170 offset:31264
	ds_read_b128 v[128:131], v170 offset:31296
	ds_read_b128 v[116:119], v170 offset:31328
	s_waitcnt lgkmcnt(8)
	v_mfma_f32_32x32x16_bf16 v[48:63], v[176:179], v[80:83], v[48:63]
	s_nop 4
	v_exp_f32_e32 v160, v64
	v_exp_f32_e32 v161, v65
	v_exp_f32_e32 v64, v66
	v_exp_f32_e32 v65, v67
	v_exp_f32_e32 v68, v68
	v_exp_f32_e32 v69, v69
	v_exp_f32_e32 v66, v70
	v_exp_f32_e32 v67, v71
	v_cvt_pk_bf16_f32 v176, v160, v161
	v_cvt_pk_bf16_f32 v177, v64, v65
	v_cvt_pk_bf16_f32 v178, v68, v69
	v_cvt_pk_bf16_f32 v179, v66, v67
	v_exp_f32_e32 v70, v74
	v_exp_f32_e32 v71, v75
	s_waitcnt lgkmcnt(0)
	v_mfma_f32_32x32x16_bf16 v[16:31], v[136:139], v[176:179], v[16:31]
	v_exp_f32_e32 v136, v72
	v_exp_f32_e32 v137, v73
	v_exp_f32_e32 v74, v76
	v_exp_f32_e32 v75, v77
	v_exp_f32_e32 v72, v78
	v_exp_f32_e32 v73, v79
	v_exp_f32_e32 v76, v48
	v_mfma_f32_32x32x16_bf16 v[0:15], v[144:147], v[176:179], v[0:15]
	v_cvt_pk_bf16_f32 v144, v136, v137
	v_cvt_pk_bf16_f32 v145, v70, v71
	v_cvt_pk_bf16_f32 v146, v74, v75
	v_cvt_pk_bf16_f32 v147, v72, v73
	v_exp_f32_e32 v77, v49
	v_exp_f32_e32 v48, v50
	v_exp_f32_e32 v49, v51
	v_mfma_f32_32x32x16_bf16 v[16:31], v[124:127], v[144:147], v[16:31]
	v_exp_f32_e32 v52, v52
	v_exp_f32_e32 v53, v53
	v_exp_f32_e32 v50, v54
	v_exp_f32_e32 v51, v55
	v_cvt_pk_bf16_f32 v124, v76, v77
	v_cvt_pk_bf16_f32 v125, v48, v49
	v_cvt_pk_bf16_f32 v126, v52, v53
	v_mfma_f32_32x32x16_bf16 v[0:15], v[140:143], v[144:147], v[0:15]
	v_cvt_pk_bf16_f32 v127, v50, v51
	v_exp_f32_e32 v78, v56
	v_exp_f32_e32 v79, v57
	v_exp_f32_e32 v54, v58
	v_exp_f32_e32 v55, v59
	v_exp_f32_e32 v58, v60
	v_exp_f32_e32 v59, v61
	v_mfma_f32_32x32x16_bf16 v[16:31], v[132:135], v[124:127], v[16:31]
	v_exp_f32_e32 v56, v62
	v_exp_f32_e32 v57, v63
	v_cvt_pk_bf16_f32 v60, v78, v79
	v_cvt_pk_bf16_f32 v61, v54, v55
	v_cvt_pk_bf16_f32 v62, v58, v59
	v_cvt_pk_bf16_f32 v63, v56, v57
	v_mfma_f32_32x32x16_bf16 v[0:15], v[128:131], v[124:127], v[0:15]
	v_mfma_f32_32x32x16_bf16 v[16:31], v[120:123], v[60:63], v[16:31]
	v_mfma_f32_32x32x16_bf16 v[0:15], v[116:119], v[60:63], v[0:15]
	s_waitcnt vmcnt(0)
	ds_write2_b64 v246, v[112:113], v[114:115] offset1:2
	v_pk_add_f32 v[48:49], v[64:65], v[48:49]
	v_pk_add_f32 v[60:61], v[160:161], v[76:77]
	v_pk_add_f32 v[48:49], v[152:153], v[48:49]
	v_pk_add_f32 v[50:51], v[66:67], v[50:51]
	v_pk_add_f32 v[60:61], v[150:151], v[60:61]
	v_pk_add_f32 v[52:53], v[68:69], v[52:53]
	v_pk_add_f32 v[48:49], v[50:51], v[48:49]
	v_pk_add_f32 v[50:51], v[70:71], v[54:55]
	v_pk_add_f32 v[52:53], v[52:53], v[60:61]
	v_pk_add_f32 v[60:61], v[136:137], v[78:79]
	v_pk_add_f32 v[48:49], v[50:51], v[48:49]
	v_pk_add_f32 v[50:51], v[72:73], v[56:57]
	v_pk_add_f32 v[52:53], v[60:61], v[52:53]
	v_pk_add_f32 v[58:59], v[74:75], v[58:59]
	v_pk_add_f32 v[152:153], v[50:51], v[48:49]
	v_pk_add_f32 v[150:151], v[58:59], v[52:53]
	s_add_i32 m0, s70, 13312
	s_waitcnt lgkmcnt(0)
	s_barrier
; #define AT_QK_LD0(kb_) do { if constexpr (NEGM) { const LAS unsigned char* kbp_ = Kl + (kb_) * KBUF + r32 * KROWB + hi * 16; AT_KLD2(0); __builtin_amdgcn_sched_barrier(0); } } while (0)
; template <int DQK, int DV, int RH, bool NEGM> ...
;     ...
;         for (int t = 0; t < NT; ++t) {
;             const int kb = t & 1;
;             if (t + 1 < NT) AT_GLOAD(t + 1);
;             f32x16 p[RH][2];
;             AT_QK_LD0(kb); AT_QK(kb); AT_VLOAD(vs_cur); AT_SOFTMAX(); AT_PV(vs_cur);
;             if (t + 1 < NT) AT_LSTORE(kb ^ 1, vs_next);
;             __syncthreads();
;             vs_prev = vs_cur; vs_cur = vs_next; vs_next = (vs_next == 2) ? 0 : vs_next + 1;
	ds_read_b128 v[48:51], v169
	ds_read_b128 v[52:55], v169 offset:32
	ds_read_b128 v[116:119], v169 offset:6656
	ds_read_b128 v[120:123], v169 offset:6688
	global_load_lds_dwordx4 v241, s[98:99]
	s_add_i32 m0, s73, s74
	global_load_dwordx4 v[112:115], v158, s[100:101] offset:384
	global_load_lds_dwordx4 v242, s[98:99]
	s_add_u32 s98, s98, 0x18000
	s_addc_u32 s99, s99, 0
	s_waitcnt lgkmcnt(3)
	v_mfma_f32_32x32x16_bf16 v[64:79], v[48:51], v[100:103], v[32:47]
	ds_read_b128 v[124:127], v169 offset:64
	ds_read_b128 v[128:131], v169 offset:96
	ds_read_b128 v[132:135], v169 offset:6720
	ds_read_b128 v[136:139], v169 offset:6752
	s_waitcnt lgkmcnt(4)
	v_mfma_f32_32x32x16_bf16 v[64:79], v[52:55], v[96:99], v[64:79]
	v_mfma_f32_32x32x16_bf16 v[48:63], v[116:119], v[100:103], v[32:47]
	v_mfma_f32_32x32x16_bf16 v[48:63], v[120:123], v[96:99], v[48:63]
	s_waitcnt lgkmcnt(1)
	v_mfma_f32_32x32x16_bf16 v[64:79], v[124:127], v[92:95], v[64:79]
	v_mfma_f32_32x32x16_bf16 v[48:63], v[132:135], v[92:95], v[48:63]
	v_mfma_f32_32x32x16_bf16 v[64:79], v[128:131], v[88:91], v[64:79]
	ds_read_b128 v[116:119], v169 offset:128
	ds_read_b128 v[120:123], v169 offset:160
	ds_read_b128 v[128:131], v169 offset:6784
	ds_read_b128 v[176:179], v169 offset:6816
	s_waitcnt lgkmcnt(3)
	v_mfma_f32_32x32x16_bf16 v[48:63], v[136:139], v[88:91], v[48:63]
	v_mfma_f32_32x32x16_bf16 v[64:79], v[116:119], v[84:87], v[64:79]
	ds_read_b128 v[136:139], v170 offset:35840
	ds_read_b128 v[124:127], v170 offset:35872
	s_waitcnt lgkmcnt(3)
	v_mfma_f32_32x32x16_bf16 v[48:63], v[128:131], v[84:87], v[48:63]
	v_mfma_f32_32x32x16_bf16 v[64:79], v[120:123], v[80:83], v[64:79]
	ds_read_b128 v[132:135], v170 offset:35904
	ds_read_b128 v[120:123], v170 offset:35936
	ds_read_b128 v[144:147], v170 offset:40448
	ds_read_b128 v[140:143], v170 offset:40480
	ds_read_b128 v[128:131], v170 offset:40512
	ds_read_b128 v[116:119], v170 offset:40544
	s_waitcnt lgkmcnt(8)
	v_mfma_f32_32x32x16_bf16 v[48:63], v[176:179], v[80:83], v[48:63]
	s_nop 4
	v_exp_f32_e32 v160, v64
	v_exp_f32_e32 v161, v65
	v_exp_f32_e32 v64, v66
	v_exp_f32_e32 v65, v67
	v_exp_f32_e32 v68, v68
	v_exp_f32_e32 v69, v69
	v_exp_f32_e32 v66, v70
	v_exp_f32_e32 v67, v71
	v_cvt_pk_bf16_f32 v176, v160, v161
	v_cvt_pk_bf16_f32 v177, v64, v65
	v_cvt_pk_bf16_f32 v178, v68, v69
	v_cvt_pk_bf16_f32 v179, v66, v67
	v_exp_f32_e32 v70, v74
	v_exp_f32_e32 v71, v75
	s_waitcnt lgkmcnt(0)
	v_mfma_f32_32x32x16_bf16 v[16:31], v[136:139], v[176:179], v[16:31]
	v_exp_f32_e32 v136, v72
	v_exp_f32_e32 v137, v73
	v_exp_f32_e32 v74, v76
	v_exp_f32_e32 v75, v77
	v_exp_f32_e32 v72, v78
	v_exp_f32_e32 v73, v79
	v_exp_f32_e32 v76, v48
	v_mfma_f32_32x32x16_bf16 v[0:15], v[144:147], v[176:179], v[0:15]
	v_cvt_pk_bf16_f32 v144, v136, v137
	v_cvt_pk_bf16_f32 v145, v70, v71
	v_cvt_pk_bf16_f32 v146, v74, v75
	v_cvt_pk_bf16_f32 v147, v72, v73
	v_exp_f32_e32 v77, v49
	v_exp_f32_e32 v48, v50
	v_exp_f32_e32 v49, v51
	v_mfma_f32_32x32x16_bf16 v[16:31], v[124:127], v[144:147], v[16:31]
	v_exp_f32_e32 v52, v52
	v_exp_f32_e32 v53, v53
	v_exp_f32_e32 v50, v54
	v_exp_f32_e32 v51, v55
	v_cvt_pk_bf16_f32 v124, v76, v77
	v_cvt_pk_bf16_f32 v125, v48, v49
	v_cvt_pk_bf16_f32 v126, v52, v53
	v_mfma_f32_32x32x16_bf16 v[0:15], v[140:143], v[144:147], v[0:15]
	v_cvt_pk_bf16_f32 v127, v50, v51
	v_exp_f32_e32 v78, v56
	v_exp_f32_e32 v79, v57
	v_exp_f32_e32 v54, v58
	v_exp_f32_e32 v55, v59
	v_exp_f32_e32 v58, v60
	v_exp_f32_e32 v59, v61
	v_mfma_f32_32x32x16_bf16 v[16:31], v[132:135], v[124:127], v[16:31]
	v_exp_f32_e32 v56, v62
	v_exp_f32_e32 v57, v63
	v_cvt_pk_bf16_f32 v60, v78, v79
	v_cvt_pk_bf16_f32 v61, v54, v55
	v_cvt_pk_bf16_f32 v62, v58, v59
	v_cvt_pk_bf16_f32 v63, v56, v57
	v_mfma_f32_32x32x16_bf16 v[0:15], v[128:131], v[124:127], v[0:15]
	v_mfma_f32_32x32x16_bf16 v[16:31], v[120:123], v[60:63], v[16:31]
	v_mfma_f32_32x32x16_bf16 v[0:15], v[116:119], v[60:63], v[0:15]
	s_waitcnt vmcnt(0)
	ds_write2_b64 v247, v[112:113], v[114:115] offset1:2
	v_pk_add_f32 v[48:49], v[64:65], v[48:49]
	v_pk_add_f32 v[60:61], v[160:161], v[76:77]
	v_pk_add_f32 v[48:49], v[152:153], v[48:49]
	v_pk_add_f32 v[50:51], v[66:67], v[50:51]
	v_pk_add_f32 v[60:61], v[150:151], v[60:61]
	v_pk_add_f32 v[52:53], v[68:69], v[52:53]
	v_pk_add_f32 v[48:49], v[50:51], v[48:49]
	v_pk_add_f32 v[50:51], v[70:71], v[54:55]
	v_pk_add_f32 v[52:53], v[52:53], v[60:61]
	v_pk_add_f32 v[60:61], v[136:137], v[78:79]
	v_pk_add_f32 v[48:49], v[50:51], v[48:49]
	v_pk_add_f32 v[50:51], v[72:73], v[56:57]
	v_pk_add_f32 v[52:53], v[60:61], v[52:53]
	v_pk_add_f32 v[58:59], v[74:75], v[58:59]
	v_pk_add_f32 v[152:153], v[50:51], v[48:49]
	v_pk_add_f32 v[150:151], v[58:59], v[52:53]
	s_mov_b32 m0, s70
	s_waitcnt lgkmcnt(0)
	s_barrier
; #define AT_QK_LD0(kb_) do { if constexpr (NEGM) { const LAS unsigned char* kbp_ = Kl + (kb_) * KBUF + r32 * KROWB + hi * 16; AT_KLD2(0); __builtin_amdgcn_sched_barrier(0); } } while (0)
; template <int DQK, int DV, int RH, bool NEGM> ...
;     ...
;         for (int t = 0; t < NT; ++t) {
;             const int kb = t & 1;
;             if (t + 1 < NT) AT_GLOAD(t + 1);
;             f32x16 p[RH][2];
;             AT_QK_LD0(kb); AT_QK(kb); AT_VLOAD(vs_cur); AT_SOFTMAX(); AT_PV(vs_cur);
;             if (t + 1 < NT) AT_LSTORE(kb ^ 1, vs_next);
;             __syncthreads();
;             vs_prev = vs_cur; vs_cur = vs_next; vs_next = (vs_next == 2) ? 0 : vs_next + 1;
	ds_read_b128 v[48:51], v169 offset:13312
	ds_read_b128 v[52:55], v169 offset:13344
	ds_read_b128 v[116:119], v169 offset:19968
	ds_read_b128 v[120:123], v169 offset:20000
	global_load_lds_dwordx4 v241, s[98:99]
	s_mov_b32 m0, s73
	global_load_dwordx4 v[112:115], v158, s[100:101] offset:512
	global_load_lds_dwordx4 v242, s[98:99]
	s_add_u32 s98, s98, 0x18000
	s_addc_u32 s99, s99, 0
	s_waitcnt lgkmcnt(3)
	v_mfma_f32_32x32x16_bf16 v[64:79], v[48:51], v[100:103], v[32:47]
	ds_read_b128 v[124:127], v169 offset:13376
	ds_read_b128 v[128:131], v169 offset:13408
	ds_read_b128 v[132:135], v169 offset:20032
	ds_read_b128 v[136:139], v169 offset:20064
	s_waitcnt lgkmcnt(4)
	v_mfma_f32_32x32x16_bf16 v[64:79], v[52:55], v[96:99], v[64:79]
	v_mfma_f32_32x32x16_bf16 v[48:63], v[116:119], v[100:103], v[32:47]
	v_mfma_f32_32x32x16_bf16 v[48:63], v[120:123], v[96:99], v[48:63]
	s_waitcnt lgkmcnt(1)
	v_mfma_f32_32x32x16_bf16 v[64:79], v[124:127], v[92:95], v[64:79]
	v_mfma_f32_32x32x16_bf16 v[48:63], v[132:135], v[92:95], v[48:63]
	v_mfma_f32_32x32x16_bf16 v[64:79], v[128:131], v[88:91], v[64:79]
	ds_read_b128 v[116:119], v169 offset:13440
	ds_read_b128 v[120:123], v169 offset:13472
	ds_read_b128 v[128:131], v169 offset:20096
	ds_read_b128 v[176:179], v169 offset:20128
	s_waitcnt lgkmcnt(3)
	v_mfma_f32_32x32x16_bf16 v[48:63], v[136:139], v[88:91], v[48:63]
	v_mfma_f32_32x32x16_bf16 v[64:79], v[116:119], v[84:87], v[64:79]
	ds_read_b128 v[136:139], v170 offset:45056
	ds_read_b128 v[124:127], v170 offset:45088
	s_waitcnt lgkmcnt(3)
	v_mfma_f32_32x32x16_bf16 v[48:63], v[128:131], v[84:87], v[48:63]
	v_mfma_f32_32x32x16_bf16 v[64:79], v[120:123], v[80:83], v[64:79]
	ds_read_b128 v[132:135], v170 offset:45120
	ds_read_b128 v[120:123], v170 offset:45152
	ds_read_b128 v[144:147], v170 offset:49664
	ds_read_b128 v[140:143], v170 offset:49696
	ds_read_b128 v[128:131], v170 offset:49728
	ds_read_b128 v[116:119], v170 offset:49760
	s_waitcnt lgkmcnt(8)
	v_mfma_f32_32x32x16_bf16 v[48:63], v[176:179], v[80:83], v[48:63]
	s_nop 4
	v_exp_f32_e32 v160, v64
	v_exp_f32_e32 v161, v65
	v_exp_f32_e32 v64, v66
	v_exp_f32_e32 v65, v67
	v_exp_f32_e32 v68, v68
	v_exp_f32_e32 v69, v69
	v_exp_f32_e32 v66, v70
	v_exp_f32_e32 v67, v71
	v_cvt_pk_bf16_f32 v176, v160, v161
	v_cvt_pk_bf16_f32 v177, v64, v65
	v_cvt_pk_bf16_f32 v178, v68, v69
	v_cvt_pk_bf16_f32 v179, v66, v67
	v_exp_f32_e32 v70, v74
	v_exp_f32_e32 v71, v75
	s_waitcnt lgkmcnt(0)
	v_mfma_f32_32x32x16_bf16 v[16:31], v[136:139], v[176:179], v[16:31]
	v_exp_f32_e32 v136, v72
	v_exp_f32_e32 v137, v73
	v_exp_f32_e32 v74, v76
	v_exp_f32_e32 v75, v77
	v_exp_f32_e32 v72, v78
	v_exp_f32_e32 v73, v79
	v_exp_f32_e32 v76, v48
	v_mfma_f32_32x32x16_bf16 v[0:15], v[144:147], v[176:179], v[0:15]
	v_cvt_pk_bf16_f32 v144, v136, v137
	v_cvt_pk_bf16_f32 v145, v70, v71
	v_cvt_pk_bf16_f32 v146, v74, v75
	v_cvt_pk_bf16_f32 v147, v72, v73
	v_exp_f32_e32 v77, v49
	v_exp_f32_e32 v48, v50
	v_exp_f32_e32 v49, v51
	v_mfma_f32_32x32x16_bf16 v[16:31], v[124:127], v[144:147], v[16:31]
	v_exp_f32_e32 v52, v52
	v_exp_f32_e32 v53, v53
	v_exp_f32_e32 v50, v54
	v_exp_f32_e32 v51, v55
	v_cvt_pk_bf16_f32 v124, v76, v77
	v_cvt_pk_bf16_f32 v125, v48, v49
	v_cvt_pk_bf16_f32 v126, v52, v53
	v_mfma_f32_32x32x16_bf16 v[0:15], v[140:143], v[144:147], v[0:15]
	v_cvt_pk_bf16_f32 v127, v50, v51
	v_exp_f32_e32 v78, v56
	v_exp_f32_e32 v79, v57
	v_exp_f32_e32 v54, v58
	v_exp_f32_e32 v55, v59
	v_exp_f32_e32 v58, v60
	v_exp_f32_e32 v59, v61
	v_mfma_f32_32x32x16_bf16 v[16:31], v[132:135], v[124:127], v[16:31]
	v_exp_f32_e32 v56, v62
	v_exp_f32_e32 v57, v63
	v_cvt_pk_bf16_f32 v60, v78, v79
	v_cvt_pk_bf16_f32 v61, v54, v55
	v_cvt_pk_bf16_f32 v62, v58, v59
	v_cvt_pk_bf16_f32 v63, v56, v57
	v_mfma_f32_32x32x16_bf16 v[0:15], v[128:131], v[124:127], v[0:15]
	v_mfma_f32_32x32x16_bf16 v[16:31], v[120:123], v[60:63], v[16:31]
	v_mfma_f32_32x32x16_bf16 v[0:15], v[116:119], v[60:63], v[0:15]
	s_waitcnt vmcnt(0)
	ds_write2_b64 v243, v[112:113], v[114:115] offset1:2
	v_pk_add_f32 v[48:49], v[64:65], v[48:49]
	v_pk_add_f32 v[60:61], v[160:161], v[76:77]
	v_pk_add_f32 v[48:49], v[152:153], v[48:49]
	v_pk_add_f32 v[50:51], v[66:67], v[50:51]
	v_pk_add_f32 v[60:61], v[150:151], v[60:61]
	v_pk_add_f32 v[52:53], v[68:69], v[52:53]
	v_pk_add_f32 v[48:49], v[50:51], v[48:49]
	v_pk_add_f32 v[50:51], v[70:71], v[54:55]
	v_pk_add_f32 v[52:53], v[52:53], v[60:61]
	v_pk_add_f32 v[60:61], v[136:137], v[78:79]
	v_pk_add_f32 v[48:49], v[50:51], v[48:49]
	v_pk_add_f32 v[50:51], v[72:73], v[56:57]
	v_pk_add_f32 v[52:53], v[60:61], v[52:53]
	v_pk_add_f32 v[58:59], v[74:75], v[58:59]
	v_pk_add_f32 v[152:153], v[50:51], v[48:49]
	v_pk_add_f32 v[150:151], v[58:59], v[52:53]
	s_add_i32 m0, s70, 13312
	s_waitcnt lgkmcnt(0)
	s_barrier
; #define AT_QK_LD0(kb_) do { if constexpr (NEGM) { const LAS unsigned char* kbp_ = Kl + (kb_) * KBUF + r32 * KROWB + hi * 16; AT_KLD2(0); __builtin_amdgcn_sched_barrier(0); } } while (0)
; template <int DQK, int DV, int RH, bool NEGM> ...
;     ...
;         for (int t = 0; t < NT; ++t) {
;             const int kb = t & 1;
;             if (t + 1 < NT) AT_GLOAD(t + 1);
;             f32x16 p[RH][2];
;             AT_QK_LD0(kb); AT_QK(kb); AT_VLOAD(vs_cur); AT_SOFTMAX(); AT_PV(vs_cur);
;             if (t + 1 < NT) AT_LSTORE(kb ^ 1, vs_next);
;             __syncthreads();
;             vs_prev = vs_cur; vs_cur = vs_next; vs_next = (vs_next == 2) ? 0 : vs_next + 1;
	ds_read_b128 v[48:51], v169
	ds_read_b128 v[52:55], v169 offset:32
	ds_read_b128 v[116:119], v169 offset:6656
	ds_read_b128 v[120:123], v169 offset:6688
	global_load_lds_dwordx4 v241, s[98:99]
	s_add_i32 m0, s73, s74
	global_load_dwordx4 v[112:115], v158, s[100:101] offset:640
	global_load_lds_dwordx4 v242, s[98:99]
	s_add_u32 s98, s98, 0x18000
	s_addc_u32 s99, s99, 0
	s_waitcnt lgkmcnt(3)
	v_mfma_f32_32x32x16_bf16 v[64:79], v[48:51], v[100:103], v[32:47]
	ds_read_b128 v[124:127], v169 offset:64
	ds_read_b128 v[128:131], v169 offset:96
	ds_read_b128 v[132:135], v169 offset:6720
	ds_read_b128 v[136:139], v169 offset:6752
	s_waitcnt lgkmcnt(4)
	v_mfma_f32_32x32x16_bf16 v[64:79], v[52:55], v[96:99], v[64:79]
	v_mfma_f32_32x32x16_bf16 v[48:63], v[116:119], v[100:103], v[32:47]
	v_mfma_f32_32x32x16_bf16 v[48:63], v[120:123], v[96:99], v[48:63]
	s_waitcnt lgkmcnt(1)
	v_mfma_f32_32x32x16_bf16 v[64:79], v[124:127], v[92:95], v[64:79]
	v_mfma_f32_32x32x16_bf16 v[48:63], v[132:135], v[92:95], v[48:63]
	v_mfma_f32_32x32x16_bf16 v[64:79], v[128:131], v[88:91], v[64:79]
	ds_read_b128 v[116:119], v169 offset:128
	ds_read_b128 v[120:123], v169 offset:160
	ds_read_b128 v[128:131], v169 offset:6784
	ds_read_b128 v[176:179], v169 offset:6816
	s_waitcnt lgkmcnt(3)
	v_mfma_f32_32x32x16_bf16 v[48:63], v[136:139], v[88:91], v[48:63]
	v_mfma_f32_32x32x16_bf16 v[64:79], v[116:119], v[84:87], v[64:79]
	ds_read_b128 v[136:139], v170 offset:26624
	ds_read_b128 v[124:127], v170 offset:26656
	s_waitcnt lgkmcnt(3)
	v_mfma_f32_32x32x16_bf16 v[48:63], v[128:131], v[84:87], v[48:63]
	v_mfma_f32_32x32x16_bf16 v[64:79], v[120:123], v[80:83], v[64:79]
	ds_read_b128 v[132:135], v170 offset:26688
	ds_read_b128 v[120:123], v170 offset:26720
	ds_read_b128 v[144:147], v170 offset:31232
	ds_read_b128 v[140:143], v170 offset:31264
	ds_read_b128 v[128:131], v170 offset:31296
	ds_read_b128 v[116:119], v170 offset:31328
	s_waitcnt lgkmcnt(8)
	v_mfma_f32_32x32x16_bf16 v[48:63], v[176:179], v[80:83], v[48:63]
	s_nop 4
	v_exp_f32_e32 v160, v64
	v_exp_f32_e32 v161, v65
	v_exp_f32_e32 v64, v66
	v_exp_f32_e32 v65, v67
	v_exp_f32_e32 v68, v68
	v_exp_f32_e32 v69, v69
	v_exp_f32_e32 v66, v70
	v_exp_f32_e32 v67, v71
	v_cvt_pk_bf16_f32 v176, v160, v161
	v_cvt_pk_bf16_f32 v177, v64, v65
	v_cvt_pk_bf16_f32 v178, v68, v69
	v_cvt_pk_bf16_f32 v179, v66, v67
	v_exp_f32_e32 v70, v74
	v_exp_f32_e32 v71, v75
	s_waitcnt lgkmcnt(0)
	v_mfma_f32_32x32x16_bf16 v[16:31], v[136:139], v[176:179], v[16:31]
	v_exp_f32_e32 v136, v72
	v_exp_f32_e32 v137, v73
	v_exp_f32_e32 v74, v76
	v_exp_f32_e32 v75, v77
	v_exp_f32_e32 v72, v78
	v_exp_f32_e32 v73, v79
	v_exp_f32_e32 v76, v48
	v_mfma_f32_32x32x16_bf16 v[0:15], v[144:147], v[176:179], v[0:15]
	v_cvt_pk_bf16_f32 v144, v136, v137
	v_cvt_pk_bf16_f32 v145, v70, v71
	v_cvt_pk_bf16_f32 v146, v74, v75
	v_cvt_pk_bf16_f32 v147, v72, v73
	v_exp_f32_e32 v77, v49
	v_exp_f32_e32 v48, v50
	v_exp_f32_e32 v49, v51
	v_mfma_f32_32x32x16_bf16 v[16:31], v[124:127], v[144:147], v[16:31]
	v_exp_f32_e32 v52, v52
	v_exp_f32_e32 v53, v53
	v_exp_f32_e32 v50, v54
	v_exp_f32_e32 v51, v55
	v_cvt_pk_bf16_f32 v124, v76, v77
	v_cvt_pk_bf16_f32 v125, v48, v49
	v_cvt_pk_bf16_f32 v126, v52, v53
	v_mfma_f32_32x32x16_bf16 v[0:15], v[140:143], v[144:147], v[0:15]
	v_cvt_pk_bf16_f32 v127, v50, v51
	v_exp_f32_e32 v78, v56
	v_exp_f32_e32 v79, v57
	v_exp_f32_e32 v54, v58
	v_exp_f32_e32 v55, v59
	v_exp_f32_e32 v58, v60
	v_exp_f32_e32 v59, v61
	v_mfma_f32_32x32x16_bf16 v[16:31], v[132:135], v[124:127], v[16:31]
	v_exp_f32_e32 v56, v62
	v_exp_f32_e32 v57, v63
	v_cvt_pk_bf16_f32 v60, v78, v79
	v_cvt_pk_bf16_f32 v61, v54, v55
	v_cvt_pk_bf16_f32 v62, v58, v59
	v_cvt_pk_bf16_f32 v63, v56, v57
	v_mfma_f32_32x32x16_bf16 v[0:15], v[128:131], v[124:127], v[0:15]
	v_mfma_f32_32x32x16_bf16 v[16:31], v[120:123], v[60:63], v[16:31]
	v_mfma_f32_32x32x16_bf16 v[0:15], v[116:119], v[60:63], v[0:15]
	s_waitcnt vmcnt(0)
	ds_write2_b64 v246, v[112:113], v[114:115] offset1:2
	v_pk_add_f32 v[48:49], v[64:65], v[48:49]
	v_pk_add_f32 v[60:61], v[160:161], v[76:77]
	v_pk_add_f32 v[48:49], v[152:153], v[48:49]
	v_pk_add_f32 v[50:51], v[66:67], v[50:51]
	v_pk_add_f32 v[60:61], v[150:151], v[60:61]
	v_pk_add_f32 v[52:53], v[68:69], v[52:53]
	v_pk_add_f32 v[48:49], v[50:51], v[48:49]
	v_pk_add_f32 v[50:51], v[70:71], v[54:55]
	v_pk_add_f32 v[52:53], v[52:53], v[60:61]
	v_pk_add_f32 v[60:61], v[136:137], v[78:79]
	v_pk_add_f32 v[48:49], v[50:51], v[48:49]
	v_pk_add_f32 v[50:51], v[72:73], v[56:57]
	v_pk_add_f32 v[52:53], v[60:61], v[52:53]
	v_pk_add_f32 v[58:59], v[74:75], v[58:59]
	v_pk_add_f32 v[152:153], v[50:51], v[48:49]
	v_pk_add_f32 v[150:151], v[58:59], v[52:53]
	s_mov_b32 m0, s70
	s_waitcnt lgkmcnt(0)
	s_barrier
	s_add_u32 s100, s100, 0x300
	s_addc_u32 s101, s101, 0
	s_add_i32 s43, s43, 6
	s_branch .Lmla_loop
